# v22 plus three s_nop 0 between an M0 write and the LDS-DMA load that follows it (wait state that a removed dead reload used to provide)
# speedup vs baseline: 1.0107x; 1.0011x over previous
.LBB0_115:
	s_andn2_b64 vcc, exec, s[0:1]
	s_cbranch_vccnz .LBB0_227
	v_lshrrev_b32_e32 v2, 1, v171
	v_and_b32_e32 v11, 24, v2
	v_lshrrev_b32_e32 v2, 5, v171
	v_and_b32_e32 v2, 4, v2
	v_bfe_u32 v3, v171, 2, 2
	v_lshlrev_b32_e32 v0, 4, v171
	v_and_b32_e32 v1, 32, v171
	v_bfe_u32 v10, v171, 2, 4
	v_or3_b32 v2, v2, v3, v11
	v_lshrrev_b32_e32 v3, 3, v171
	s_movk_i32 s0, 0x70
	v_bitop3_b32 v8, v0, v1, 48 bitop3:0x6c
	v_and_b32_e32 v9, 64, v171
	v_and_or_b32 v4, v3, s0, v10
	s_movk_i32 s0, 0x60
	v_add_u32_e32 v12, 0x2000, v0
	s_add_u32 s15, s76, 0xc00000
	v_or_b32_e32 v1, v8, v9
	v_and_or_b32 v3, v3, s0, v2
	v_lshrrev_b32_e32 v0, 7, v12
	s_movk_i32 s0, 0xf0
	s_addc_u32 s30, s77, 0
	v_lshl_or_b32 v138, v3, 11, v1
	v_and_or_b32 v3, v0, s0, v10
	s_movk_i32 s0, 0xe0
	s_lshr_b32 s1, s12, 6
	s_ashr_i32 s5, s4, 31
	s_ashr_i32 s25, s24, 31
	v_and_or_b32 v0, v0, s0, v2
	s_lshr_b32 s0, s12, 8
	s_lshl_b32 s31, s1, 10
	s_lshl_b64 s[2:3], s[4:5], 19
	s_lshl_b64 s[8:9], s[24:25], 19
	s_add_u32 s26, s15, s8
	s_addc_u32 s27, s30, s9
	s_add_i32 s34, s31, 0
	s_add_i32 m0, s34, 0x10000
	v_lshl_or_b32 v142, v0, 11, v1
	global_load_lds_dwordx4 v138, s[26:27]
	s_add_i32 m0, s34, 0x12000
	s_add_u32 s8, s26, 0x40000
	global_load_lds_dwordx4 v142, s[26:27]
	s_addc_u32 s9, s27, 0
	s_add_i32 m0, s34, 0x14000
	s_nop 0
	global_load_lds_dwordx4 v138, s[8:9]
	s_add_i32 m0, s34, 0x16000
	v_readlane_b32 s70, v246, 34
	v_readlane_b32 s71, v246, 35
	s_add_u32 s2, s70, s2
	s_addc_u32 s3, s71, s3
	s_add_i32 s35, s34, 0x2000
	v_lshl_or_b32 v136, v4, 11, v1
	global_load_lds_dwordx4 v142, s[8:9]
	s_mov_b32 m0, s34
	s_add_u32 s8, s2, 0x40000
	v_lshl_or_b32 v140, v3, 11, v1
	global_load_lds_dwordx4 v136, s[2:3]
	s_mov_b32 m0, s35
	s_addc_u32 s9, s3, 0
	s_add_i32 s36, s34, 0x4000
	global_load_lds_dwordx4 v140, s[2:3]
	s_mov_b32 m0, s36
	s_add_i32 s37, s34, 0x6000
	global_load_lds_dwordx4 v136, s[8:9]
	s_mov_b32 m0, s37
	v_mov_b32_e32 v139, 0
	global_load_lds_dwordx4 v140, s[8:9]
	v_mov_b32_e32 v143, v139
	v_mov_b32_e32 v137, v139
	v_mov_b32_e32 v141, v139
	s_cmp_eq_u32 s0, 1
	s_mov_b32 s38, 0
	v_lshl_add_u64 v[6:7], s[26:27], 0, v[138:139]
	v_lshl_add_u64 v[4:5], s[26:27], 0, v[142:143]
	v_lshl_add_u64 v[0:1], s[2:3], 0, v[136:137]
	s_cselect_b64 s[8:9], -1, 0
	s_cmp_lg_u32 s0, 1
	v_lshl_add_u64 v[2:3], s[2:3], 0, v[140:141]
	s_cbranch_scc1 .LBB0_118
	s_barrier

.LBB0_447:
	s_cmp_lt_i32 s78, 5
	s_cselect_b64 s[2:3], -1, 0
	s_and_b64 s[2:3], s[2:3], s[0:1]
	s_andn2_b64 vcc, exec, s[2:3]
	s_cbranch_vccnz .LBB0_469
	s_mov_b32 s87, 0
	s_mov_b32 s32, 0
	s_mov_b32 s85, 0
	s_cmpk_gt_i32 s74, 0x47f
	v_readfirstlane_b32 s1, v171
	s_cbranch_scc1 .LBB0_464
	v_lshrrev_b32_e32 v2, 1, v171
	v_and_b32_e32 v11, 24, v2
	v_lshrrev_b32_e32 v2, 5, v171
	v_and_b32_e32 v2, 4, v2
	v_bfe_u32 v3, v171, 2, 2
	v_lshlrev_b32_e32 v0, 4, v171
	v_and_b32_e32 v1, 32, v171
	v_bfe_u32 v10, v171, 2, 4
	v_or3_b32 v2, v2, v3, v11
	v_lshrrev_b32_e32 v3, 3, v171
	s_movk_i32 s0, 0x70
	v_bitop3_b32 v8, v0, v1, 48 bitop3:0x6c
	v_and_b32_e32 v9, 64, v171
	v_and_or_b32 v4, v3, s0, v10
	s_movk_i32 s0, 0x60
	v_add_u32_e32 v12, 0x2000, v0
	v_or_b32_e32 v1, v8, v9
	v_and_or_b32 v3, v3, s0, v2
	v_lshrrev_b32_e32 v0, 7, v12
	s_movk_i32 s0, 0xf0
	v_lshl_or_b32 v130, v3, 11, v1
	v_and_or_b32 v3, v0, s0, v10
	s_movk_i32 s0, 0xe0
	s_ashr_i32 s27, s74, 31
	v_and_or_b32 v0, v0, s0, v2
	s_lshr_b32 s0, s27, 29
	s_add_i32 s0, s74, s0
	s_lshr_b32 s6, s1, 6
	s_ashr_i32 s4, s0, 3
	s_and_b32 s0, s0, -8
	s_lshr_b32 s8, s1, 8
	s_lshl_b32 s26, s6, 10
	s_sub_i32 s0, s74, s0
	s_cmp_lt_i32 s0, 0
	s_movk_i32 s28, 0x91
	s_cselect_b32 s5, s28, 0x90
	s_mul_i32 s0, s0, s5
	s_add_i32 s0, s0, s4
	s_mul_hi_i32 s4, s0, 0x38e38e39
	s_lshr_b32 s5, s4, 31
	s_ashr_i32 s4, s4, 5
	s_add_i32 s4, s4, s5
	s_lshl_b32 s5, s4, 3
	s_mulk_i32 s4, 0x90
	s_sub_i32 s4, s0, s4
	s_sext_i32_i16 s0, s4
	s_bfe_u32 s0, s0, 0x3001c
	s_add_i32 s7, s4, s0
	s_sext_i32_i16 s0, s7
	s_and_b32 s7, s7, 0xfff8
	s_sub_i32 s4, s4, s7
	s_sext_i32_i16 s4, s4
	s_lshr_b32 s0, s0, 3
	s_add_i32 s18, s5, s4
	s_ashr_i32 s19, s18, 31
	s_bfe_i64 s[10:11], s[0:1], 0x100000
	s_lshl_b64 s[4:5], s[18:19], 19
	s_lshl_b64 s[10:11], s[10:11], 19
	v_readlane_b32 s12, v246, 36
	v_readlane_b32 s13, v246, 37
	s_add_u32 s22, s12, s10
	s_addc_u32 s23, s13, s11
	s_add_i32 s19, s26, 0
	s_add_i32 m0, s19, 0x10000
	v_lshl_or_b32 v134, v0, 11, v1
	global_load_lds_dwordx4 v130, s[22:23]
	s_add_i32 m0, s19, 0x12000
	s_add_u32 s10, s22, 0x40000
	global_load_lds_dwordx4 v134, s[22:23]
	s_addc_u32 s11, s23, 0
	s_add_i32 m0, s19, 0x14000
	s_nop 0
	global_load_lds_dwordx4 v130, s[10:11]
	s_add_i32 m0, s19, 0x16000
	v_readlane_b32 s50, v246, 34
	v_readlane_b32 s51, v246, 35
	s_add_u32 s20, s50, s4
	s_addc_u32 s21, s51, s5
	s_add_i32 s29, s19, 0x2000
	v_lshl_or_b32 v128, v4, 11, v1
	global_load_lds_dwordx4 v134, s[10:11]
	s_mov_b32 m0, s19
	s_add_u32 s4, s20, 0x40000
	v_lshl_or_b32 v132, v3, 11, v1
	global_load_lds_dwordx4 v128, s[20:21]
	s_mov_b32 m0, s29
	s_addc_u32 s5, s21, 0
	s_add_i32 s30, s19, 0x4000
	global_load_lds_dwordx4 v132, s[20:21]
	s_mov_b32 m0, s30
	s_add_i32 s31, s19, 0x6000
	global_load_lds_dwordx4 v128, s[4:5]
	s_mov_b32 m0, s31
	v_mov_b32_e32 v131, 0
	global_load_lds_dwordx4 v132, s[4:5]
	v_mov_b32_e32 v135, v131
	v_mov_b32_e32 v129, v131
	v_mov_b32_e32 v133, v131
	s_cmp_eq_u32 s8, 1
	s_mov_b32 s33, 0
	v_lshl_add_u64 v[6:7], s[22:23], 0, v[130:131]
	v_lshl_add_u64 v[4:5], s[22:23], 0, v[134:135]
	v_lshl_add_u64 v[0:1], s[20:21], 0, v[128:129]
	s_cselect_b64 s[4:5], -1, 0
	s_cmp_lg_u32 s8, 1
	v_lshl_add_u64 v[2:3], s[20:21], 0, v[132:133]
	s_cbranch_scc1 .LBB0_451
	s_barrier

.LBB0_932:
	s_cmp_lt_i32 s78, 11
	s_cselect_b64 s[2:3], -1, 0
	s_and_b64 s[2:3], s[2:3], s[0:1]
	s_andn2_b64 vcc, exec, s[2:3]
	s_cbranch_vccnz .LBB0_949
	s_cmpk_gt_i32 s74, 0x57f
	v_readfirstlane_b32 s1, v171
	s_cbranch_scc1 .LBB0_949
	v_lshrrev_b32_e32 v1, 1, v171
	v_and_b32_e32 v9, 24, v1
	v_lshrrev_b32_e32 v1, 5, v171
	v_bitop3_b32 v8, v176, v178, 48 bitop3:0x6c
	v_and_b32_e32 v1, 4, v1
	v_bfe_u32 v2, v171, 2, 2
	s_movk_i32 s0, 0x70
	v_or_b32_e32 v0, v8, v173
	v_or3_b32 v1, v1, v2, v9
	v_and_or_b32 v2, v177, s0, v175
	s_movk_i32 s0, 0x60
	v_add_u32_e32 v10, 0x2000, v176
	v_and_or_b32 v3, v177, s0, v1
	v_lshl_or_b32 v128, v2, 11, v0
	v_lshrrev_b32_e32 v2, 7, v10
	s_movk_i32 s0, 0xf0
	v_lshl_or_b32 v130, v3, 11, v0
	v_and_or_b32 v3, v2, s0, v175
	s_movk_i32 s0, 0xe0
	s_ashr_i32 s29, s74, 31
	v_and_or_b32 v1, v2, s0, v1
	s_lshr_b32 s0, s29, 29
	s_add_i32 s0, s74, s0
	s_lshr_b32 s8, s1, 6
	s_ashr_i32 s4, s0, 3
	s_and_b32 s0, s0, -8
	s_lshr_b32 s10, s1, 8
	s_lshl_b32 s28, s8, 10
	s_sub_i32 s0, s74, s0
	s_cmp_lt_i32 s0, 0
	s_movk_i32 s30, 0xb1
	s_cselect_b32 s5, s30, 0xb0
	s_mul_i32 s0, s0, s5
	s_add_i32 s0, s0, s4
	s_mul_hi_i32 s4, s0, 0x2e8ba2e9
	s_lshr_b32 s5, s4, 31
	s_ashr_i32 s4, s4, 5
	s_add_i32 s4, s4, s5
	s_lshl_b32 s5, s4, 3
	s_mulk_i32 s4, 0xb0
	s_sub_i32 s4, s0, s4
	s_sext_i32_i16 s0, s4
	s_bfe_u32 s0, s0, 0x3001c
	s_add_i32 s9, s4, s0
	s_sext_i32_i16 s0, s9
	s_and_b32 s9, s9, 0xfff8
	s_sub_i32 s4, s4, s9
	s_sext_i32_i16 s4, s4
	s_lshr_b32 s0, s0, 3
	s_add_i32 s20, s5, s4
	s_ashr_i32 s21, s20, 31
	s_bfe_i64 s[12:13], s[0:1], 0x100000
	s_lshl_b64 s[4:5], s[20:21], 19
	s_lshl_b64 s[12:13], s[12:13], 19
	v_readlane_b32 s14, v246, 44
	v_readlane_b32 s15, v246, 45
	s_add_u32 s24, s14, s12
	s_addc_u32 s25, s15, s13
	s_add_i32 s21, s28, 0
	s_add_i32 m0, s21, 0x10000
	s_nop 0
	global_load_lds_dwordx4 v130, s[24:25]
	s_add_i32 m0, s21, 0x12000
	v_lshl_or_b32 v134, v1, 11, v0
	s_add_u32 s12, s24, 0x40000
	v_readlane_b32 s48, v246, 32
	v_readlane_b32 s49, v246, 33
	global_load_lds_dwordx4 v134, s[24:25]
	s_addc_u32 s13, s25, 0
	s_add_i32 m0, s21, 0x14000
	v_readlane_b32 s50, v246, 34
	v_readlane_b32 s51, v246, 35
	s_mov_b64 s[16:17], s[48:49]
	global_load_lds_dwordx4 v130, s[12:13]
	s_add_i32 m0, s21, 0x16000
	s_mov_b64 s[18:19], s[50:51]
	s_add_u32 s22, s18, s4
	s_addc_u32 s23, s19, s5
	s_add_i32 s31, s21, 0x2000
	global_load_lds_dwordx4 v134, s[12:13]
	s_mov_b32 m0, s21
	s_add_u32 s4, s22, 0x40000
	v_lshl_or_b32 v132, v3, 11, v0
	global_load_lds_dwordx4 v128, s[22:23]
	s_mov_b32 m0, s31
	s_addc_u32 s5, s23, 0
	s_add_i32 s33, s21, 0x4000
	global_load_lds_dwordx4 v132, s[22:23]
	s_mov_b32 m0, s33
	s_add_i32 s34, s21, 0x6000
	global_load_lds_dwordx4 v128, s[4:5]
	s_mov_b32 m0, s34
	v_mov_b32_e32 v131, 0
	global_load_lds_dwordx4 v132, s[4:5]
	v_mov_b32_e32 v135, v131
	v_mov_b32_e32 v129, v131
	v_mov_b32_e32 v133, v131
	s_cmp_eq_u32 s10, 1
	s_mov_b32 s35, 0
	v_lshl_add_u64 v[6:7], s[24:25], 0, v[130:131]
	v_lshl_add_u64 v[4:5], s[24:25], 0, v[134:135]
	v_lshl_add_u64 v[0:1], s[22:23], 0, v[128:129]
	s_cselect_b64 s[4:5], -1, 0
	s_cmp_lg_u32 s10, 1
	v_lshl_add_u64 v[2:3], s[22:23], 0, v[132:133]
	s_cbranch_scc1 .LBB0_936
	s_barrier
